# attention tile loop: 8-tile chunk fully unrolled with static tile indices, no per-tile latch logic or conditional prefetch branches, bias reads with immediate offsets
# baseline (speedup 1.0000x reference)
; DI void dsa_attn_item(const Params& p, int b, int qblk, char* smem) {
;     ...
;     for (int t8 = 0; t8 < 8; ++t8) {
;       const int g = c * 8 + t8;
;       if (g > qblk) break;
;       {
;         const int gn = min(g + 1, qblk);
;         const u16* kr = kfr + (size_t)gn * 2048;
; #pragma unroll
;         for (int ks = 0; ks < 4; ++ks) Kn[ks] = ldg8(kr + ks * 512);
; #pragma unroll
;         for (int dt = 0; dt < 2; ++dt)
; #pragma unroll
;           for (int s = 0; s < 2; ++s) Vn[dt][s] = ldg8(vfr + (size_t)gn * 2048 + (dt * 2 + s) * 512);
;       }
;       const unsigned bits = maskbuf[(buf * 8 + t8) * 64 + lane];
;       f32x16 Sx = zero16();
;       __builtin_amdgcn_s_setprio(1);
; #pragma unroll
;       for (int ks = 0; ks < 4; ++ks) Sx = MFMA(Kf[ks], Qf[ks], Sx);
;       __builtin_amdgcn_s_setprio(0);
;       float sm[16];
; #pragma unroll
;       for (int i = 0; i < 16; ++i) {
;         const unsigned t = (unsigned)__builtin_amdgcn_sbfe((int)bits, i, 1);
;         sm[i] = __uint_as_float((t & __float_as_uint(Sx[i])) | (~t & 0xff800000u));
;       }
;       float mt = fmaxf(fmaxf(fmaxf(sm[0], sm[1]), fmaxf(sm[2], sm[3])), fmaxf(fmaxf(sm[4], sm[5]), fmaxf(sm[6], sm[7])));
;       mt = fmaxf(mt, fmaxf(fmaxf(fmaxf(sm[8], sm[9]), fmaxf(sm[10], sm[11])), fmaxf(fmaxf(sm[12], sm[13]), fmaxf(sm[14], sm[15]))));
;       mt = fmaxf(mt, __shfl_xor(mt, 32));
;       if (__builtin_amdgcn_ballot_w64(mt > mrun + 8.f) != 0ull) {
;         const float mnew = fmaxf(mrun, mt);
;         const float ms = (mnew == -INFINITY) ? 0.f : mnew;
;         const float alpha = __builtin_amdgcn_exp2f(mrun - ms);
;         lrun *= alpha;
;         mrun = mnew;
; #pragma unroll
;         for (int dt = 0; dt < 2; ++dt)
; #pragma unroll
;           for (int i = 0; i < 16; ++i) O[dt][i] *= alpha;
;       }
;       const float msafe = (mrun == -INFINITY) ? 0.f : mrun;
;       float pv[16]; float ps = 0.f;
; #pragma unroll
;       for (int i = 0; i < 16; ++i) { pv[i] = __builtin_amdgcn_exp2f(sm[i] - msafe); ps += pv[i]; }
;       lrun += ps;
;       bf16x8 Pf[2];
; #pragma unroll
;       for (int s = 0; s < 2; ++s) Pf[s] = pack8(pv[8 * s], pv[8 * s + 1], pv[8 * s + 2], pv[8 * s + 3], pv[8 * s + 4], pv[8 * s + 5], pv[8 * s + 6], pv[8 * s + 7]);
;       __builtin_amdgcn_s_setprio(1);
; #pragma unroll
;       for (int dt = 0; dt < 2; ++dt)
; #pragma unroll
.LBB0_439:
	ds_read_b128 v[238:241], v0
	ds_read_b128 v[242:245], v0 offset:1024
	ds_read_b128 v[246:249], v0 offset:2048
	ds_read_b128 v[250:253], v0 offset:3072
	s_add_i32 s60, s53, 1
	s_min_i32 s40, s60, s52
	s_lshl_b64 s[10:11], s[40:41], 12
	v_lshl_add_u64 v[160:161], v[198:199], 0, s[10:11]
	global_load_dwordx4 v[66:69], v[160:161], off
	global_load_dwordx4 v[70:73], v[160:161], off offset:1024
	global_load_dwordx4 v[74:77], v[160:161], off offset:2048
	global_load_dwordx4 v[78:81], v[160:161], off offset:3072
	v_lshl_add_u64 v[160:161], v[200:201], 0, s[10:11]
	global_load_dwordx4 v[50:53], v[160:161], off
	global_load_dwordx4 v[54:57], v[160:161], off offset:1024
	global_load_dwordx4 v[58:61], v[160:161], off offset:2048
	global_load_dwordx4 v[62:65], v[160:161], off offset:3072
	s_mov_b32 s7, s53
	s_cmp_gt_u32 s7, s52
	s_cbranch_scc1 .LBB0_446
	s_add_i32 s60, s7, 2
	s_min_i32 s40, s60, s52
	s_lshl_b64 s[10:11], s[40:41], 12
	s_waitcnt vmcnt(12) lgkmcnt(0)
	s_setprio 1
	v_mfma_f32_32x32x16_bf16 v[34:49], v[150:153], v[98:101], v[238:253]
	v_mfma_f32_32x32x16_bf16 v[34:49], v[146:149], v[102:105], v[34:49]
	v_mfma_f32_32x32x16_bf16 v[34:49], v[142:145], v[106:109], v[34:49]
	v_mfma_f32_32x32x16_bf16 v[34:49], v[138:141], v[110:113], v[34:49]
	s_setprio 0
	v_lshl_add_u64 v[160:161], v[198:199], 0, s[10:11]
	ds_read_b128 v[238:241], v0 offset:4096
	ds_read_b128 v[242:245], v0 offset:5120
	ds_read_b128 v[246:249], v0 offset:6144
	ds_read_b128 v[250:253], v0 offset:7168
	global_load_dwordx4 v[150:153], v[160:161], off
	global_load_dwordx4 v[146:149], v[160:161], off offset:1024
	global_load_dwordx4 v[142:145], v[160:161], off offset:2048
	global_load_dwordx4 v[138:141], v[160:161], off offset:3072
	s_nop 7
	s_nop 3
	v_max_f32_e32 v154, v36, v37
	v_max_f32_e32 v155, v40, v41
	v_max_f32_e32 v156, v42, v43
	v_max_f32_e32 v157, v44, v45
	v_max_f32_e32 v158, v48, v49
	v_max3_f32 v158, v46, v47, v158
	v_max3_f32 v154, v34, v35, v154
	v_max3_f32 v155, v38, v39, v155
	v_max3_f32 v156, v156, v157, v158
	v_max3_f32 v154, v154, v155, v156
	v_mov_b32_e32 v155, v154
	s_nop 1
	v_permlane32_swap_b32_e32 v155, v154
	v_max_f32_e32 v154, v154, v155
	v_cmp_gt_f32_e32 vcc, v154, v229
	s_cbranch_vccz .Lattn_442T0
	v_max_f32_e32 v154, v154, v154
	v_max_f32_e32 v155, v193, v193
	v_max_f32_e32 v155, v155, v154
	v_cmp_neq_f32_e32 vcc, s50, v155
	v_add_f32_e32 v229, 0x41000000, v155
	s_nop 0
	v_cndmask_b32_e32 v162, 0, v155, vcc
	v_sub_f32_e32 v154, v193, v162
	v_exp_f32_e32 v154, v154
	v_mov_b32_e32 v193, v155
	v_pk_mul_f32 v[32:33], v[32:33], v[154:155] op_sel_hi:[1,0]
	v_pk_mul_f32 v[30:31], v[30:31], v[154:155] op_sel_hi:[1,0]
	v_pk_mul_f32 v[28:29], v[28:29], v[154:155] op_sel_hi:[1,0]
	v_pk_mul_f32 v[26:27], v[26:27], v[154:155] op_sel_hi:[1,0]
	v_pk_mul_f32 v[24:25], v[24:25], v[154:155] op_sel_hi:[1,0]
	v_pk_mul_f32 v[22:23], v[22:23], v[154:155] op_sel_hi:[1,0]
	v_pk_mul_f32 v[20:21], v[20:21], v[154:155] op_sel_hi:[1,0]
	v_pk_mul_f32 v[18:19], v[18:19], v[154:155] op_sel_hi:[1,0]
	v_pk_mul_f32 v[16:17], v[16:17], v[154:155] op_sel_hi:[1,0]
	v_pk_mul_f32 v[14:15], v[14:15], v[154:155] op_sel_hi:[1,0]
	v_pk_mul_f32 v[12:13], v[12:13], v[154:155] op_sel_hi:[1,0]
	v_pk_mul_f32 v[10:11], v[10:11], v[154:155] op_sel_hi:[1,0]
	v_pk_mul_f32 v[8:9], v[8:9], v[154:155] op_sel_hi:[1,0]
	v_pk_mul_f32 v[6:7], v[6:7], v[154:155] op_sel_hi:[1,0]
	v_pk_mul_f32 v[4:5], v[4:5], v[154:155] op_sel_hi:[1,0]
	v_pk_mul_f32 v[2:3], v[2:3], v[154:155] op_sel_hi:[1,0]
	v_mul_f32_e32 v171, v171, v154
.Lattn_442T0:
	v_pk_add_f32 v[34:35], v[34:35], v[162:163] op_sel_hi:[1,0] neg_lo:[0,1] neg_hi:[0,1]
	v_pk_add_f32 v[36:37], v[36:37], v[162:163] op_sel_hi:[1,0] neg_lo:[0,1] neg_hi:[0,1]
	v_pk_add_f32 v[38:39], v[38:39], v[162:163] op_sel_hi:[1,0] neg_lo:[0,1] neg_hi:[0,1]
	v_pk_add_f32 v[40:41], v[40:41], v[162:163] op_sel_hi:[1,0] neg_lo:[0,1] neg_hi:[0,1]
	v_pk_add_f32 v[42:43], v[42:43], v[162:163] op_sel_hi:[1,0] neg_lo:[0,1] neg_hi:[0,1]
	v_pk_add_f32 v[44:45], v[44:45], v[162:163] op_sel_hi:[1,0] neg_lo:[0,1] neg_hi:[0,1]
	v_pk_add_f32 v[46:47], v[46:47], v[162:163] op_sel_hi:[1,0] neg_lo:[0,1] neg_hi:[0,1]
	v_pk_add_f32 v[48:49], v[48:49], v[162:163] op_sel_hi:[1,0] neg_lo:[0,1] neg_hi:[0,1]
	v_exp_f32_e32 v34, v34
	v_exp_f32_e32 v35, v35
	v_exp_f32_e32 v36, v36
	v_exp_f32_e32 v37, v37
	v_exp_f32_e32 v38, v38
	v_exp_f32_e32 v39, v39
	v_exp_f32_e32 v40, v40
	v_exp_f32_e32 v41, v41
	v_exp_f32_e32 v42, v42
	v_exp_f32_e32 v43, v43
	v_exp_f32_e32 v44, v44
	v_exp_f32_e32 v45, v45
	v_exp_f32_e32 v46, v46
	v_exp_f32_e32 v47, v47
	v_exp_f32_e32 v48, v48
	v_exp_f32_e32 v49, v49
	v_pk_add_f32 v[154:155], v[34:35], v[36:37]
	v_pk_add_f32 v[156:157], v[38:39], v[40:41]
	v_pk_add_f32 v[158:159], v[42:43], v[44:45]
	v_pk_add_f32 v[160:161], v[46:47], v[48:49]
	v_cvt_pk_bf16_f32 v34, v34, v35
	v_cvt_pk_bf16_f32 v35, v36, v37
	v_cvt_pk_bf16_f32 v36, v38, v39
	v_cvt_pk_bf16_f32 v37, v40, v41
	v_cvt_pk_bf16_f32 v38, v42, v43
	v_cvt_pk_bf16_f32 v39, v44, v45
	v_cvt_pk_bf16_f32 v40, v46, v47
	v_cvt_pk_bf16_f32 v41, v48, v49
	v_pk_add_f32 v[154:155], v[154:155], v[156:157]
	v_pk_add_f32 v[158:159], v[158:159], v[160:161]
	s_nop 0
	v_pk_add_f32 v[154:155], v[154:155], v[158:159]
	s_nop 0
	v_add_f32_e32 v154, v154, v155
	s_waitcnt vmcnt(8)
	v_add_f32_e32 v171, v171, v154
	s_setprio 1
	v_mfma_f32_32x32x16_bf16 v[18:33], v[126:129], v[34:37], v[18:33]
	v_mfma_f32_32x32x16_bf16 v[2:17], v[118:121], v[34:37], v[2:17]
	v_mfma_f32_32x32x16_bf16 v[18:33], v[122:125], v[38:41], v[18:33]
	v_mfma_f32_32x32x16_bf16 v[2:17], v[114:117], v[38:41], v[2:17]
	s_setprio 0
	v_lshl_add_u64 v[160:161], v[200:201], 0, s[10:11]
	global_load_dwordx4 v[126:129], v[160:161], off
	global_load_dwordx4 v[122:125], v[160:161], off offset:1024
	global_load_dwordx4 v[118:121], v[160:161], off offset:2048
	global_load_dwordx4 v[114:117], v[160:161], off offset:3072
	s_add_i32 s7, s53, 1
	s_cmp_gt_u32 s7, s52
	s_cbranch_scc1 .LBB0_446
; DI void dsa_attn_item(const Params& p, int b, int qblk, char* smem) {
;     ...
;     for (int t8 = 0; t8 < 8; ++t8) {
;       const int g = c * 8 + t8;
;       if (g > qblk) break;
;       {
;         const int gn = min(g + 1, qblk);
;         const u16* kr = kfr + (size_t)gn * 2048;
; #pragma unroll
;         for (int ks = 0; ks < 4; ++ks) Kn[ks] = ldg8(kr + ks * 512);
; #pragma unroll
;         for (int dt = 0; dt < 2; ++dt)
; #pragma unroll
;           for (int s = 0; s < 2; ++s) Vn[dt][s] = ldg8(vfr + (size_t)gn * 2048 + (dt * 2 + s) * 512);
;       }
;       const unsigned bits = maskbuf[(buf * 8 + t8) * 64 + lane];
;       f32x16 Sx = zero16();
;       __builtin_amdgcn_s_setprio(1);
; #pragma unroll
;       for (int ks = 0; ks < 4; ++ks) Sx = MFMA(Kf[ks], Qf[ks], Sx);
;       __builtin_amdgcn_s_setprio(0);
;       float sm[16];
; #pragma unroll
;       for (int i = 0; i < 16; ++i) {
;         const unsigned t = (unsigned)__builtin_amdgcn_sbfe((int)bits, i, 1);
;         sm[i] = __uint_as_float((t & __float_as_uint(Sx[i])) | (~t & 0xff800000u));
;       }
;       float mt = fmaxf(fmaxf(fmaxf(sm[0], sm[1]), fmaxf(sm[2], sm[3])), fmaxf(fmaxf(sm[4], sm[5]), fmaxf(sm[6], sm[7])));
;       mt = fmaxf(mt, fmaxf(fmaxf(fmaxf(sm[8], sm[9]), fmaxf(sm[10], sm[11])), fmaxf(fmaxf(sm[12], sm[13]), fmaxf(sm[14], sm[15]))));
;       mt = fmaxf(mt, __shfl_xor(mt, 32));
;       if (__builtin_amdgcn_ballot_w64(mt > mrun + 8.f) != 0ull) {
;         const float mnew = fmaxf(mrun, mt);
;         const float ms = (mnew == -INFINITY) ? 0.f : mnew;
;         const float alpha = __builtin_amdgcn_exp2f(mrun - ms);
;         lrun *= alpha;
;         mrun = mnew;
; #pragma unroll
;         for (int dt = 0; dt < 2; ++dt)
; #pragma unroll
;           for (int i = 0; i < 16; ++i) O[dt][i] *= alpha;
;       }
;       const float msafe = (mrun == -INFINITY) ? 0.f : mrun;
;       float pv[16]; float ps = 0.f;
; #pragma unroll
;       for (int i = 0; i < 16; ++i) { pv[i] = __builtin_amdgcn_exp2f(sm[i] - msafe); ps += pv[i]; }
;       lrun += ps;
;       bf16x8 Pf[2];
; #pragma unroll
;       for (int s = 0; s < 2; ++s) Pf[s] = pack8(pv[8 * s], pv[8 * s + 1], pv[8 * s + 2], pv[8 * s + 3], pv[8 * s + 4], pv[8 * s + 5], pv[8 * s + 6], pv[8 * s + 7]);
;       __builtin_amdgcn_s_setprio(1);
; #pragma unroll
;       for (int dt = 0; dt < 2; ++dt)
; #pragma unroll
	s_add_i32 s60, s7, 2
	s_min_i32 s40, s60, s52
	s_lshl_b64 s[10:11], s[40:41], 12
	s_waitcnt vmcnt(12) lgkmcnt(0)
	s_setprio 1
	v_mfma_f32_32x32x16_bf16 v[34:49], v[66:69], v[98:101], v[238:253]
	v_mfma_f32_32x32x16_bf16 v[34:49], v[70:73], v[102:105], v[34:49]
	v_mfma_f32_32x32x16_bf16 v[34:49], v[74:77], v[106:109], v[34:49]
	v_mfma_f32_32x32x16_bf16 v[34:49], v[78:81], v[110:113], v[34:49]
	s_setprio 0
	v_lshl_add_u64 v[160:161], v[198:199], 0, s[10:11]
	ds_read_b128 v[238:241], v0 offset:8192
	ds_read_b128 v[242:245], v0 offset:9216
	ds_read_b128 v[246:249], v0 offset:10240
	ds_read_b128 v[250:253], v0 offset:11264
	global_load_dwordx4 v[66:69], v[160:161], off
	global_load_dwordx4 v[70:73], v[160:161], off offset:1024
	global_load_dwordx4 v[74:77], v[160:161], off offset:2048
	global_load_dwordx4 v[78:81], v[160:161], off offset:3072
	s_nop 7
	s_nop 3
	v_max_f32_e32 v154, v36, v37
	v_max_f32_e32 v155, v40, v41
	v_max_f32_e32 v156, v42, v43
	v_max_f32_e32 v157, v44, v45
	v_max_f32_e32 v158, v48, v49
	v_max3_f32 v158, v46, v47, v158
	v_max3_f32 v154, v34, v35, v154
	v_max3_f32 v155, v38, v39, v155
	v_max3_f32 v156, v156, v157, v158
	v_max3_f32 v154, v154, v155, v156
	v_mov_b32_e32 v155, v154
	s_nop 1
	v_permlane32_swap_b32_e32 v155, v154
	v_max_f32_e32 v154, v154, v155
	v_cmp_gt_f32_e32 vcc, v154, v229
	s_cbranch_vccz .Lattn_442T1
	v_max_f32_e32 v154, v154, v154
	v_max_f32_e32 v155, v193, v193
	v_max_f32_e32 v155, v155, v154
	v_cmp_neq_f32_e32 vcc, s50, v155
	v_add_f32_e32 v229, 0x41000000, v155
	s_nop 0
	v_cndmask_b32_e32 v162, 0, v155, vcc
	v_sub_f32_e32 v154, v193, v162
	v_exp_f32_e32 v154, v154
	v_mov_b32_e32 v193, v155
	v_pk_mul_f32 v[32:33], v[32:33], v[154:155] op_sel_hi:[1,0]
	v_pk_mul_f32 v[30:31], v[30:31], v[154:155] op_sel_hi:[1,0]
	v_pk_mul_f32 v[28:29], v[28:29], v[154:155] op_sel_hi:[1,0]
	v_pk_mul_f32 v[26:27], v[26:27], v[154:155] op_sel_hi:[1,0]
	v_pk_mul_f32 v[24:25], v[24:25], v[154:155] op_sel_hi:[1,0]
	v_pk_mul_f32 v[22:23], v[22:23], v[154:155] op_sel_hi:[1,0]
	v_pk_mul_f32 v[20:21], v[20:21], v[154:155] op_sel_hi:[1,0]
	v_pk_mul_f32 v[18:19], v[18:19], v[154:155] op_sel_hi:[1,0]
	v_pk_mul_f32 v[16:17], v[16:17], v[154:155] op_sel_hi:[1,0]
	v_pk_mul_f32 v[14:15], v[14:15], v[154:155] op_sel_hi:[1,0]
	v_pk_mul_f32 v[12:13], v[12:13], v[154:155] op_sel_hi:[1,0]
	v_pk_mul_f32 v[10:11], v[10:11], v[154:155] op_sel_hi:[1,0]
	v_pk_mul_f32 v[8:9], v[8:9], v[154:155] op_sel_hi:[1,0]
	v_pk_mul_f32 v[6:7], v[6:7], v[154:155] op_sel_hi:[1,0]
	v_pk_mul_f32 v[4:5], v[4:5], v[154:155] op_sel_hi:[1,0]
	v_pk_mul_f32 v[2:3], v[2:3], v[154:155] op_sel_hi:[1,0]
	v_mul_f32_e32 v171, v171, v154
.Lattn_442T1:
	v_pk_add_f32 v[34:35], v[34:35], v[162:163] op_sel_hi:[1,0] neg_lo:[0,1] neg_hi:[0,1]
	v_pk_add_f32 v[36:37], v[36:37], v[162:163] op_sel_hi:[1,0] neg_lo:[0,1] neg_hi:[0,1]
	v_pk_add_f32 v[38:39], v[38:39], v[162:163] op_sel_hi:[1,0] neg_lo:[0,1] neg_hi:[0,1]
	v_pk_add_f32 v[40:41], v[40:41], v[162:163] op_sel_hi:[1,0] neg_lo:[0,1] neg_hi:[0,1]
	v_pk_add_f32 v[42:43], v[42:43], v[162:163] op_sel_hi:[1,0] neg_lo:[0,1] neg_hi:[0,1]
	v_pk_add_f32 v[44:45], v[44:45], v[162:163] op_sel_hi:[1,0] neg_lo:[0,1] neg_hi:[0,1]
	v_pk_add_f32 v[46:47], v[46:47], v[162:163] op_sel_hi:[1,0] neg_lo:[0,1] neg_hi:[0,1]
	v_pk_add_f32 v[48:49], v[48:49], v[162:163] op_sel_hi:[1,0] neg_lo:[0,1] neg_hi:[0,1]
	v_exp_f32_e32 v34, v34
	v_exp_f32_e32 v35, v35
	v_exp_f32_e32 v36, v36
	v_exp_f32_e32 v37, v37
	v_exp_f32_e32 v38, v38
	v_exp_f32_e32 v39, v39
	v_exp_f32_e32 v40, v40
	v_exp_f32_e32 v41, v41
	v_exp_f32_e32 v42, v42
	v_exp_f32_e32 v43, v43
	v_exp_f32_e32 v44, v44
	v_exp_f32_e32 v45, v45
	v_exp_f32_e32 v46, v46
	v_exp_f32_e32 v47, v47
	v_exp_f32_e32 v48, v48
	v_exp_f32_e32 v49, v49
	v_pk_add_f32 v[154:155], v[34:35], v[36:37]
	v_pk_add_f32 v[156:157], v[38:39], v[40:41]
	v_pk_add_f32 v[158:159], v[42:43], v[44:45]
	v_pk_add_f32 v[160:161], v[46:47], v[48:49]
	v_cvt_pk_bf16_f32 v34, v34, v35
	v_cvt_pk_bf16_f32 v35, v36, v37
	v_cvt_pk_bf16_f32 v36, v38, v39
	v_cvt_pk_bf16_f32 v37, v40, v41
	v_cvt_pk_bf16_f32 v38, v42, v43
	v_cvt_pk_bf16_f32 v39, v44, v45
	v_cvt_pk_bf16_f32 v40, v46, v47
	v_cvt_pk_bf16_f32 v41, v48, v49
	v_pk_add_f32 v[154:155], v[154:155], v[156:157]
	v_pk_add_f32 v[158:159], v[158:159], v[160:161]
	s_nop 0
	v_pk_add_f32 v[154:155], v[154:155], v[158:159]
	s_nop 0
	v_add_f32_e32 v154, v154, v155
	s_waitcnt vmcnt(8)
	v_add_f32_e32 v171, v171, v154
	s_setprio 1
	v_mfma_f32_32x32x16_bf16 v[18:33], v[50:53], v[34:37], v[18:33]
	v_mfma_f32_32x32x16_bf16 v[2:17], v[58:61], v[34:37], v[2:17]
	v_mfma_f32_32x32x16_bf16 v[18:33], v[54:57], v[38:41], v[18:33]
	v_mfma_f32_32x32x16_bf16 v[2:17], v[62:65], v[38:41], v[2:17]
	s_setprio 0
	v_lshl_add_u64 v[160:161], v[200:201], 0, s[10:11]
	global_load_dwordx4 v[50:53], v[160:161], off
	global_load_dwordx4 v[54:57], v[160:161], off offset:1024
	global_load_dwordx4 v[58:61], v[160:161], off offset:2048
	global_load_dwordx4 v[62:65], v[160:161], off offset:3072
	s_add_i32 s7, s53, 2
	s_cmp_gt_u32 s7, s52
	s_cbranch_scc1 .LBB0_446
; DI void dsa_attn_item(const Params& p, int b, int qblk, char* smem) {
;     ...
;     for (int t8 = 0; t8 < 8; ++t8) {
;       const int g = c * 8 + t8;
;       if (g > qblk) break;
;       {
;         const int gn = min(g + 1, qblk);
;         const u16* kr = kfr + (size_t)gn * 2048;
; #pragma unroll
;         for (int ks = 0; ks < 4; ++ks) Kn[ks] = ldg8(kr + ks * 512);
; #pragma unroll
;         for (int dt = 0; dt < 2; ++dt)
; #pragma unroll
;           for (int s = 0; s < 2; ++s) Vn[dt][s] = ldg8(vfr + (size_t)gn * 2048 + (dt * 2 + s) * 512);
;       }
;       const unsigned bits = maskbuf[(buf * 8 + t8) * 64 + lane];
;       f32x16 Sx = zero16();
;       __builtin_amdgcn_s_setprio(1);
; #pragma unroll
;       for (int ks = 0; ks < 4; ++ks) Sx = MFMA(Kf[ks], Qf[ks], Sx);
;       __builtin_amdgcn_s_setprio(0);
;       float sm[16];
; #pragma unroll
;       for (int i = 0; i < 16; ++i) {
;         const unsigned t = (unsigned)__builtin_amdgcn_sbfe((int)bits, i, 1);
;         sm[i] = __uint_as_float((t & __float_as_uint(Sx[i])) | (~t & 0xff800000u));
;       }
;       float mt = fmaxf(fmaxf(fmaxf(sm[0], sm[1]), fmaxf(sm[2], sm[3])), fmaxf(fmaxf(sm[4], sm[5]), fmaxf(sm[6], sm[7])));
;       mt = fmaxf(mt, fmaxf(fmaxf(fmaxf(sm[8], sm[9]), fmaxf(sm[10], sm[11])), fmaxf(fmaxf(sm[12], sm[13]), fmaxf(sm[14], sm[15]))));
;       mt = fmaxf(mt, __shfl_xor(mt, 32));
;       if (__builtin_amdgcn_ballot_w64(mt > mrun + 8.f) != 0ull) {
;         const float mnew = fmaxf(mrun, mt);
;         const float ms = (mnew == -INFINITY) ? 0.f : mnew;
;         const float alpha = __builtin_amdgcn_exp2f(mrun - ms);
;         lrun *= alpha;
;         mrun = mnew;
; #pragma unroll
;         for (int dt = 0; dt < 2; ++dt)
; #pragma unroll
;           for (int i = 0; i < 16; ++i) O[dt][i] *= alpha;
;       }
;       const float msafe = (mrun == -INFINITY) ? 0.f : mrun;
;       float pv[16]; float ps = 0.f;
; #pragma unroll
;       for (int i = 0; i < 16; ++i) { pv[i] = __builtin_amdgcn_exp2f(sm[i] - msafe); ps += pv[i]; }
;       lrun += ps;
;       bf16x8 Pf[2];
; #pragma unroll
;       for (int s = 0; s < 2; ++s) Pf[s] = pack8(pv[8 * s], pv[8 * s + 1], pv[8 * s + 2], pv[8 * s + 3], pv[8 * s + 4], pv[8 * s + 5], pv[8 * s + 6], pv[8 * s + 7]);
;       __builtin_amdgcn_s_setprio(1);
; #pragma unroll
;       for (int dt = 0; dt < 2; ++dt)
; #pragma unroll
	s_add_i32 s60, s7, 2
	s_min_i32 s40, s60, s52
	s_lshl_b64 s[10:11], s[40:41], 12
	s_waitcnt vmcnt(12) lgkmcnt(0)
	s_setprio 1
	v_mfma_f32_32x32x16_bf16 v[34:49], v[150:153], v[98:101], v[238:253]
	v_mfma_f32_32x32x16_bf16 v[34:49], v[146:149], v[102:105], v[34:49]
	v_mfma_f32_32x32x16_bf16 v[34:49], v[142:145], v[106:109], v[34:49]
	v_mfma_f32_32x32x16_bf16 v[34:49], v[138:141], v[110:113], v[34:49]
	s_setprio 0
	v_lshl_add_u64 v[160:161], v[198:199], 0, s[10:11]
	ds_read_b128 v[238:241], v0 offset:12288
	ds_read_b128 v[242:245], v0 offset:13312
	ds_read_b128 v[246:249], v0 offset:14336
	ds_read_b128 v[250:253], v0 offset:15360
	global_load_dwordx4 v[150:153], v[160:161], off
	global_load_dwordx4 v[146:149], v[160:161], off offset:1024
	global_load_dwordx4 v[142:145], v[160:161], off offset:2048
	global_load_dwordx4 v[138:141], v[160:161], off offset:3072
	s_nop 7
	s_nop 3
	v_max_f32_e32 v154, v36, v37
	v_max_f32_e32 v155, v40, v41
	v_max_f32_e32 v156, v42, v43
	v_max_f32_e32 v157, v44, v45
	v_max_f32_e32 v158, v48, v49
	v_max3_f32 v158, v46, v47, v158
	v_max3_f32 v154, v34, v35, v154
	v_max3_f32 v155, v38, v39, v155
	v_max3_f32 v156, v156, v157, v158
	v_max3_f32 v154, v154, v155, v156
	v_mov_b32_e32 v155, v154
	s_nop 1
	v_permlane32_swap_b32_e32 v155, v154
	v_max_f32_e32 v154, v154, v155
	v_cmp_gt_f32_e32 vcc, v154, v229
	s_cbranch_vccz .Lattn_442T2
	v_max_f32_e32 v154, v154, v154
	v_max_f32_e32 v155, v193, v193
	v_max_f32_e32 v155, v155, v154
	v_cmp_neq_f32_e32 vcc, s50, v155
	v_add_f32_e32 v229, 0x41000000, v155
	s_nop 0
	v_cndmask_b32_e32 v162, 0, v155, vcc
	v_sub_f32_e32 v154, v193, v162
	v_exp_f32_e32 v154, v154
	v_mov_b32_e32 v193, v155
	v_pk_mul_f32 v[32:33], v[32:33], v[154:155] op_sel_hi:[1,0]
	v_pk_mul_f32 v[30:31], v[30:31], v[154:155] op_sel_hi:[1,0]
	v_pk_mul_f32 v[28:29], v[28:29], v[154:155] op_sel_hi:[1,0]
	v_pk_mul_f32 v[26:27], v[26:27], v[154:155] op_sel_hi:[1,0]
	v_pk_mul_f32 v[24:25], v[24:25], v[154:155] op_sel_hi:[1,0]
	v_pk_mul_f32 v[22:23], v[22:23], v[154:155] op_sel_hi:[1,0]
	v_pk_mul_f32 v[20:21], v[20:21], v[154:155] op_sel_hi:[1,0]
	v_pk_mul_f32 v[18:19], v[18:19], v[154:155] op_sel_hi:[1,0]
	v_pk_mul_f32 v[16:17], v[16:17], v[154:155] op_sel_hi:[1,0]
	v_pk_mul_f32 v[14:15], v[14:15], v[154:155] op_sel_hi:[1,0]
	v_pk_mul_f32 v[12:13], v[12:13], v[154:155] op_sel_hi:[1,0]
	v_pk_mul_f32 v[10:11], v[10:11], v[154:155] op_sel_hi:[1,0]
	v_pk_mul_f32 v[8:9], v[8:9], v[154:155] op_sel_hi:[1,0]
	v_pk_mul_f32 v[6:7], v[6:7], v[154:155] op_sel_hi:[1,0]
	v_pk_mul_f32 v[4:5], v[4:5], v[154:155] op_sel_hi:[1,0]
	v_pk_mul_f32 v[2:3], v[2:3], v[154:155] op_sel_hi:[1,0]
	v_mul_f32_e32 v171, v171, v154
.Lattn_442T2:
	v_pk_add_f32 v[34:35], v[34:35], v[162:163] op_sel_hi:[1,0] neg_lo:[0,1] neg_hi:[0,1]
	v_pk_add_f32 v[36:37], v[36:37], v[162:163] op_sel_hi:[1,0] neg_lo:[0,1] neg_hi:[0,1]
	v_pk_add_f32 v[38:39], v[38:39], v[162:163] op_sel_hi:[1,0] neg_lo:[0,1] neg_hi:[0,1]
	v_pk_add_f32 v[40:41], v[40:41], v[162:163] op_sel_hi:[1,0] neg_lo:[0,1] neg_hi:[0,1]
	v_pk_add_f32 v[42:43], v[42:43], v[162:163] op_sel_hi:[1,0] neg_lo:[0,1] neg_hi:[0,1]
	v_pk_add_f32 v[44:45], v[44:45], v[162:163] op_sel_hi:[1,0] neg_lo:[0,1] neg_hi:[0,1]
	v_pk_add_f32 v[46:47], v[46:47], v[162:163] op_sel_hi:[1,0] neg_lo:[0,1] neg_hi:[0,1]
	v_pk_add_f32 v[48:49], v[48:49], v[162:163] op_sel_hi:[1,0] neg_lo:[0,1] neg_hi:[0,1]
	v_exp_f32_e32 v34, v34
	v_exp_f32_e32 v35, v35
	v_exp_f32_e32 v36, v36
	v_exp_f32_e32 v37, v37
	v_exp_f32_e32 v38, v38
	v_exp_f32_e32 v39, v39
	v_exp_f32_e32 v40, v40
	v_exp_f32_e32 v41, v41
	v_exp_f32_e32 v42, v42
	v_exp_f32_e32 v43, v43
	v_exp_f32_e32 v44, v44
	v_exp_f32_e32 v45, v45
	v_exp_f32_e32 v46, v46
	v_exp_f32_e32 v47, v47
	v_exp_f32_e32 v48, v48
	v_exp_f32_e32 v49, v49
	v_pk_add_f32 v[154:155], v[34:35], v[36:37]
	v_pk_add_f32 v[156:157], v[38:39], v[40:41]
	v_pk_add_f32 v[158:159], v[42:43], v[44:45]
	v_pk_add_f32 v[160:161], v[46:47], v[48:49]
	v_cvt_pk_bf16_f32 v34, v34, v35
	v_cvt_pk_bf16_f32 v35, v36, v37
	v_cvt_pk_bf16_f32 v36, v38, v39
	v_cvt_pk_bf16_f32 v37, v40, v41
	v_cvt_pk_bf16_f32 v38, v42, v43
	v_cvt_pk_bf16_f32 v39, v44, v45
	v_cvt_pk_bf16_f32 v40, v46, v47
	v_cvt_pk_bf16_f32 v41, v48, v49
	v_pk_add_f32 v[154:155], v[154:155], v[156:157]
	v_pk_add_f32 v[158:159], v[158:159], v[160:161]
	s_nop 0
	v_pk_add_f32 v[154:155], v[154:155], v[158:159]
	s_nop 0
	v_add_f32_e32 v154, v154, v155
	s_waitcnt vmcnt(8)
	v_add_f32_e32 v171, v171, v154
	s_setprio 1
	v_mfma_f32_32x32x16_bf16 v[18:33], v[126:129], v[34:37], v[18:33]
	v_mfma_f32_32x32x16_bf16 v[2:17], v[118:121], v[34:37], v[2:17]
	v_mfma_f32_32x32x16_bf16 v[18:33], v[122:125], v[38:41], v[18:33]
	v_mfma_f32_32x32x16_bf16 v[2:17], v[114:117], v[38:41], v[2:17]
	s_setprio 0
	v_lshl_add_u64 v[160:161], v[200:201], 0, s[10:11]
	global_load_dwordx4 v[126:129], v[160:161], off
	global_load_dwordx4 v[122:125], v[160:161], off offset:1024
	global_load_dwordx4 v[118:121], v[160:161], off offset:2048
	global_load_dwordx4 v[114:117], v[160:161], off offset:3072
	s_add_i32 s7, s53, 3
	s_cmp_gt_u32 s7, s52
	s_cbranch_scc1 .LBB0_446
; DI void dsa_attn_item(const Params& p, int b, int qblk, char* smem) {
;     ...
;     for (int t8 = 0; t8 < 8; ++t8) {
;       const int g = c * 8 + t8;
;       if (g > qblk) break;
;       {
;         const int gn = min(g + 1, qblk);
;         const u16* kr = kfr + (size_t)gn * 2048;
; #pragma unroll
;         for (int ks = 0; ks < 4; ++ks) Kn[ks] = ldg8(kr + ks * 512);
; #pragma unroll
;         for (int dt = 0; dt < 2; ++dt)
; #pragma unroll
;           for (int s = 0; s < 2; ++s) Vn[dt][s] = ldg8(vfr + (size_t)gn * 2048 + (dt * 2 + s) * 512);
;       }
;       const unsigned bits = maskbuf[(buf * 8 + t8) * 64 + lane];
;       f32x16 Sx = zero16();
;       __builtin_amdgcn_s_setprio(1);
; #pragma unroll
;       for (int ks = 0; ks < 4; ++ks) Sx = MFMA(Kf[ks], Qf[ks], Sx);
;       __builtin_amdgcn_s_setprio(0);
;       float sm[16];
; #pragma unroll
;       for (int i = 0; i < 16; ++i) {
;         const unsigned t = (unsigned)__builtin_amdgcn_sbfe((int)bits, i, 1);
;         sm[i] = __uint_as_float((t & __float_as_uint(Sx[i])) | (~t & 0xff800000u));
;       }
;       float mt = fmaxf(fmaxf(fmaxf(sm[0], sm[1]), fmaxf(sm[2], sm[3])), fmaxf(fmaxf(sm[4], sm[5]), fmaxf(sm[6], sm[7])));
;       mt = fmaxf(mt, fmaxf(fmaxf(fmaxf(sm[8], sm[9]), fmaxf(sm[10], sm[11])), fmaxf(fmaxf(sm[12], sm[13]), fmaxf(sm[14], sm[15]))));
;       mt = fmaxf(mt, __shfl_xor(mt, 32));
;       if (__builtin_amdgcn_ballot_w64(mt > mrun + 8.f) != 0ull) {
;         const float mnew = fmaxf(mrun, mt);
;         const float ms = (mnew == -INFINITY) ? 0.f : mnew;
;         const float alpha = __builtin_amdgcn_exp2f(mrun - ms);
;         lrun *= alpha;
;         mrun = mnew;
; #pragma unroll
;         for (int dt = 0; dt < 2; ++dt)
; #pragma unroll
;           for (int i = 0; i < 16; ++i) O[dt][i] *= alpha;
;       }
;       const float msafe = (mrun == -INFINITY) ? 0.f : mrun;
;       float pv[16]; float ps = 0.f;
; #pragma unroll
;       for (int i = 0; i < 16; ++i) { pv[i] = __builtin_amdgcn_exp2f(sm[i] - msafe); ps += pv[i]; }
;       lrun += ps;
;       bf16x8 Pf[2];
; #pragma unroll
;       for (int s = 0; s < 2; ++s) Pf[s] = pack8(pv[8 * s], pv[8 * s + 1], pv[8 * s + 2], pv[8 * s + 3], pv[8 * s + 4], pv[8 * s + 5], pv[8 * s + 6], pv[8 * s + 7]);
;       __builtin_amdgcn_s_setprio(1);
; #pragma unroll
;       for (int dt = 0; dt < 2; ++dt)
; #pragma unroll
	s_add_i32 s60, s7, 2
	s_min_i32 s40, s60, s52
	s_lshl_b64 s[10:11], s[40:41], 12
	s_waitcnt vmcnt(12) lgkmcnt(0)
	s_setprio 1
	v_mfma_f32_32x32x16_bf16 v[34:49], v[66:69], v[98:101], v[238:253]
	v_mfma_f32_32x32x16_bf16 v[34:49], v[70:73], v[102:105], v[34:49]
	v_mfma_f32_32x32x16_bf16 v[34:49], v[74:77], v[106:109], v[34:49]
	v_mfma_f32_32x32x16_bf16 v[34:49], v[78:81], v[110:113], v[34:49]
	s_setprio 0
	v_lshl_add_u64 v[160:161], v[198:199], 0, s[10:11]
	ds_read_b128 v[238:241], v0 offset:16384
	ds_read_b128 v[242:245], v0 offset:17408
	ds_read_b128 v[246:249], v0 offset:18432
	ds_read_b128 v[250:253], v0 offset:19456
	global_load_dwordx4 v[66:69], v[160:161], off
	global_load_dwordx4 v[70:73], v[160:161], off offset:1024
	global_load_dwordx4 v[74:77], v[160:161], off offset:2048
	global_load_dwordx4 v[78:81], v[160:161], off offset:3072
	s_nop 7
	s_nop 3
	v_max_f32_e32 v154, v36, v37
	v_max_f32_e32 v155, v40, v41
	v_max_f32_e32 v156, v42, v43
	v_max_f32_e32 v157, v44, v45
	v_max_f32_e32 v158, v48, v49
	v_max3_f32 v158, v46, v47, v158
	v_max3_f32 v154, v34, v35, v154
	v_max3_f32 v155, v38, v39, v155
	v_max3_f32 v156, v156, v157, v158
	v_max3_f32 v154, v154, v155, v156
	v_mov_b32_e32 v155, v154
	s_nop 1
	v_permlane32_swap_b32_e32 v155, v154
	v_max_f32_e32 v154, v154, v155
	v_cmp_gt_f32_e32 vcc, v154, v229
	s_cbranch_vccz .Lattn_442T3
	v_max_f32_e32 v154, v154, v154
	v_max_f32_e32 v155, v193, v193
	v_max_f32_e32 v155, v155, v154
	v_cmp_neq_f32_e32 vcc, s50, v155
	v_add_f32_e32 v229, 0x41000000, v155
	s_nop 0
	v_cndmask_b32_e32 v162, 0, v155, vcc
	v_sub_f32_e32 v154, v193, v162
	v_exp_f32_e32 v154, v154
	v_mov_b32_e32 v193, v155
	v_pk_mul_f32 v[32:33], v[32:33], v[154:155] op_sel_hi:[1,0]
	v_pk_mul_f32 v[30:31], v[30:31], v[154:155] op_sel_hi:[1,0]
	v_pk_mul_f32 v[28:29], v[28:29], v[154:155] op_sel_hi:[1,0]
	v_pk_mul_f32 v[26:27], v[26:27], v[154:155] op_sel_hi:[1,0]
	v_pk_mul_f32 v[24:25], v[24:25], v[154:155] op_sel_hi:[1,0]
	v_pk_mul_f32 v[22:23], v[22:23], v[154:155] op_sel_hi:[1,0]
	v_pk_mul_f32 v[20:21], v[20:21], v[154:155] op_sel_hi:[1,0]
	v_pk_mul_f32 v[18:19], v[18:19], v[154:155] op_sel_hi:[1,0]
	v_pk_mul_f32 v[16:17], v[16:17], v[154:155] op_sel_hi:[1,0]
	v_pk_mul_f32 v[14:15], v[14:15], v[154:155] op_sel_hi:[1,0]
	v_pk_mul_f32 v[12:13], v[12:13], v[154:155] op_sel_hi:[1,0]
	v_pk_mul_f32 v[10:11], v[10:11], v[154:155] op_sel_hi:[1,0]
	v_pk_mul_f32 v[8:9], v[8:9], v[154:155] op_sel_hi:[1,0]
	v_pk_mul_f32 v[6:7], v[6:7], v[154:155] op_sel_hi:[1,0]
	v_pk_mul_f32 v[4:5], v[4:5], v[154:155] op_sel_hi:[1,0]
	v_pk_mul_f32 v[2:3], v[2:3], v[154:155] op_sel_hi:[1,0]
	v_mul_f32_e32 v171, v171, v154
.Lattn_442T3:
	v_pk_add_f32 v[34:35], v[34:35], v[162:163] op_sel_hi:[1,0] neg_lo:[0,1] neg_hi:[0,1]
	v_pk_add_f32 v[36:37], v[36:37], v[162:163] op_sel_hi:[1,0] neg_lo:[0,1] neg_hi:[0,1]
	v_pk_add_f32 v[38:39], v[38:39], v[162:163] op_sel_hi:[1,0] neg_lo:[0,1] neg_hi:[0,1]
	v_pk_add_f32 v[40:41], v[40:41], v[162:163] op_sel_hi:[1,0] neg_lo:[0,1] neg_hi:[0,1]
	v_pk_add_f32 v[42:43], v[42:43], v[162:163] op_sel_hi:[1,0] neg_lo:[0,1] neg_hi:[0,1]
	v_pk_add_f32 v[44:45], v[44:45], v[162:163] op_sel_hi:[1,0] neg_lo:[0,1] neg_hi:[0,1]
	v_pk_add_f32 v[46:47], v[46:47], v[162:163] op_sel_hi:[1,0] neg_lo:[0,1] neg_hi:[0,1]
	v_pk_add_f32 v[48:49], v[48:49], v[162:163] op_sel_hi:[1,0] neg_lo:[0,1] neg_hi:[0,1]
	v_exp_f32_e32 v34, v34
	v_exp_f32_e32 v35, v35
	v_exp_f32_e32 v36, v36
	v_exp_f32_e32 v37, v37
	v_exp_f32_e32 v38, v38
	v_exp_f32_e32 v39, v39
	v_exp_f32_e32 v40, v40
	v_exp_f32_e32 v41, v41
	v_exp_f32_e32 v42, v42
	v_exp_f32_e32 v43, v43
	v_exp_f32_e32 v44, v44
	v_exp_f32_e32 v45, v45
	v_exp_f32_e32 v46, v46
	v_exp_f32_e32 v47, v47
	v_exp_f32_e32 v48, v48
	v_exp_f32_e32 v49, v49
	v_pk_add_f32 v[154:155], v[34:35], v[36:37]
	v_pk_add_f32 v[156:157], v[38:39], v[40:41]
	v_pk_add_f32 v[158:159], v[42:43], v[44:45]
	v_pk_add_f32 v[160:161], v[46:47], v[48:49]
	v_cvt_pk_bf16_f32 v34, v34, v35
	v_cvt_pk_bf16_f32 v35, v36, v37
	v_cvt_pk_bf16_f32 v36, v38, v39
	v_cvt_pk_bf16_f32 v37, v40, v41
	v_cvt_pk_bf16_f32 v38, v42, v43
	v_cvt_pk_bf16_f32 v39, v44, v45
	v_cvt_pk_bf16_f32 v40, v46, v47
	v_cvt_pk_bf16_f32 v41, v48, v49
	v_pk_add_f32 v[154:155], v[154:155], v[156:157]
	v_pk_add_f32 v[158:159], v[158:159], v[160:161]
	s_nop 0
	v_pk_add_f32 v[154:155], v[154:155], v[158:159]
	s_nop 0
	v_add_f32_e32 v154, v154, v155
	s_waitcnt vmcnt(8)
	v_add_f32_e32 v171, v171, v154
	s_setprio 1
	v_mfma_f32_32x32x16_bf16 v[18:33], v[50:53], v[34:37], v[18:33]
	v_mfma_f32_32x32x16_bf16 v[2:17], v[58:61], v[34:37], v[2:17]
	v_mfma_f32_32x32x16_bf16 v[18:33], v[54:57], v[38:41], v[18:33]
	v_mfma_f32_32x32x16_bf16 v[2:17], v[62:65], v[38:41], v[2:17]
	s_setprio 0
	v_lshl_add_u64 v[160:161], v[200:201], 0, s[10:11]
	global_load_dwordx4 v[50:53], v[160:161], off
	global_load_dwordx4 v[54:57], v[160:161], off offset:1024
	global_load_dwordx4 v[58:61], v[160:161], off offset:2048
	global_load_dwordx4 v[62:65], v[160:161], off offset:3072
	s_add_i32 s7, s53, 4
	s_cmp_gt_u32 s7, s52
	s_cbranch_scc1 .LBB0_446
; DI void dsa_attn_item(const Params& p, int b, int qblk, char* smem) {
;     ...
;     for (int t8 = 0; t8 < 8; ++t8) {
;       const int g = c * 8 + t8;
;       if (g > qblk) break;
;       {
;         const int gn = min(g + 1, qblk);
;         const u16* kr = kfr + (size_t)gn * 2048;
; #pragma unroll
;         for (int ks = 0; ks < 4; ++ks) Kn[ks] = ldg8(kr + ks * 512);
; #pragma unroll
;         for (int dt = 0; dt < 2; ++dt)
; #pragma unroll
;           for (int s = 0; s < 2; ++s) Vn[dt][s] = ldg8(vfr + (size_t)gn * 2048 + (dt * 2 + s) * 512);
;       }
;       const unsigned bits = maskbuf[(buf * 8 + t8) * 64 + lane];
;       f32x16 Sx = zero16();
;       __builtin_amdgcn_s_setprio(1);
; #pragma unroll
;       for (int ks = 0; ks < 4; ++ks) Sx = MFMA(Kf[ks], Qf[ks], Sx);
;       __builtin_amdgcn_s_setprio(0);
;       float sm[16];
; #pragma unroll
;       for (int i = 0; i < 16; ++i) {
;         const unsigned t = (unsigned)__builtin_amdgcn_sbfe((int)bits, i, 1);
;         sm[i] = __uint_as_float((t & __float_as_uint(Sx[i])) | (~t & 0xff800000u));
;       }
;       float mt = fmaxf(fmaxf(fmaxf(sm[0], sm[1]), fmaxf(sm[2], sm[3])), fmaxf(fmaxf(sm[4], sm[5]), fmaxf(sm[6], sm[7])));
;       mt = fmaxf(mt, fmaxf(fmaxf(fmaxf(sm[8], sm[9]), fmaxf(sm[10], sm[11])), fmaxf(fmaxf(sm[12], sm[13]), fmaxf(sm[14], sm[15]))));
;       mt = fmaxf(mt, __shfl_xor(mt, 32));
;       if (__builtin_amdgcn_ballot_w64(mt > mrun + 8.f) != 0ull) {
;         const float mnew = fmaxf(mrun, mt);
;         const float ms = (mnew == -INFINITY) ? 0.f : mnew;
;         const float alpha = __builtin_amdgcn_exp2f(mrun - ms);
;         lrun *= alpha;
;         mrun = mnew;
; #pragma unroll
;         for (int dt = 0; dt < 2; ++dt)
; #pragma unroll
;           for (int i = 0; i < 16; ++i) O[dt][i] *= alpha;
;       }
;       const float msafe = (mrun == -INFINITY) ? 0.f : mrun;
;       float pv[16]; float ps = 0.f;
; #pragma unroll
;       for (int i = 0; i < 16; ++i) { pv[i] = __builtin_amdgcn_exp2f(sm[i] - msafe); ps += pv[i]; }
;       lrun += ps;
;       bf16x8 Pf[2];
; #pragma unroll
;       for (int s = 0; s < 2; ++s) Pf[s] = pack8(pv[8 * s], pv[8 * s + 1], pv[8 * s + 2], pv[8 * s + 3], pv[8 * s + 4], pv[8 * s + 5], pv[8 * s + 6], pv[8 * s + 7]);
;       __builtin_amdgcn_s_setprio(1);
; #pragma unroll
;       for (int dt = 0; dt < 2; ++dt)
; #pragma unroll
	s_add_i32 s60, s7, 2
	s_min_i32 s40, s60, s52
	s_lshl_b64 s[10:11], s[40:41], 12
	s_waitcnt vmcnt(12) lgkmcnt(0)
	s_setprio 1
	v_mfma_f32_32x32x16_bf16 v[34:49], v[150:153], v[98:101], v[238:253]
	v_mfma_f32_32x32x16_bf16 v[34:49], v[146:149], v[102:105], v[34:49]
	v_mfma_f32_32x32x16_bf16 v[34:49], v[142:145], v[106:109], v[34:49]
	v_mfma_f32_32x32x16_bf16 v[34:49], v[138:141], v[110:113], v[34:49]
	s_setprio 0
	v_lshl_add_u64 v[160:161], v[198:199], 0, s[10:11]
	ds_read_b128 v[238:241], v0 offset:20480
	ds_read_b128 v[242:245], v0 offset:21504
	ds_read_b128 v[246:249], v0 offset:22528
	ds_read_b128 v[250:253], v0 offset:23552
	global_load_dwordx4 v[150:153], v[160:161], off
	global_load_dwordx4 v[146:149], v[160:161], off offset:1024
	global_load_dwordx4 v[142:145], v[160:161], off offset:2048
	global_load_dwordx4 v[138:141], v[160:161], off offset:3072
	s_nop 7
	s_nop 3
	v_max_f32_e32 v154, v36, v37
	v_max_f32_e32 v155, v40, v41
	v_max_f32_e32 v156, v42, v43
	v_max_f32_e32 v157, v44, v45
	v_max_f32_e32 v158, v48, v49
	v_max3_f32 v158, v46, v47, v158
	v_max3_f32 v154, v34, v35, v154
	v_max3_f32 v155, v38, v39, v155
	v_max3_f32 v156, v156, v157, v158
	v_max3_f32 v154, v154, v155, v156
	v_mov_b32_e32 v155, v154
	s_nop 1
	v_permlane32_swap_b32_e32 v155, v154
	v_max_f32_e32 v154, v154, v155
	v_cmp_gt_f32_e32 vcc, v154, v229
	s_cbranch_vccz .Lattn_442T4
	v_max_f32_e32 v154, v154, v154
	v_max_f32_e32 v155, v193, v193
	v_max_f32_e32 v155, v155, v154
	v_cmp_neq_f32_e32 vcc, s50, v155
	v_add_f32_e32 v229, 0x41000000, v155
	s_nop 0
	v_cndmask_b32_e32 v162, 0, v155, vcc
	v_sub_f32_e32 v154, v193, v162
	v_exp_f32_e32 v154, v154
	v_mov_b32_e32 v193, v155
	v_pk_mul_f32 v[32:33], v[32:33], v[154:155] op_sel_hi:[1,0]
	v_pk_mul_f32 v[30:31], v[30:31], v[154:155] op_sel_hi:[1,0]
	v_pk_mul_f32 v[28:29], v[28:29], v[154:155] op_sel_hi:[1,0]
	v_pk_mul_f32 v[26:27], v[26:27], v[154:155] op_sel_hi:[1,0]
	v_pk_mul_f32 v[24:25], v[24:25], v[154:155] op_sel_hi:[1,0]
	v_pk_mul_f32 v[22:23], v[22:23], v[154:155] op_sel_hi:[1,0]
	v_pk_mul_f32 v[20:21], v[20:21], v[154:155] op_sel_hi:[1,0]
	v_pk_mul_f32 v[18:19], v[18:19], v[154:155] op_sel_hi:[1,0]
	v_pk_mul_f32 v[16:17], v[16:17], v[154:155] op_sel_hi:[1,0]
	v_pk_mul_f32 v[14:15], v[14:15], v[154:155] op_sel_hi:[1,0]
	v_pk_mul_f32 v[12:13], v[12:13], v[154:155] op_sel_hi:[1,0]
	v_pk_mul_f32 v[10:11], v[10:11], v[154:155] op_sel_hi:[1,0]
	v_pk_mul_f32 v[8:9], v[8:9], v[154:155] op_sel_hi:[1,0]
	v_pk_mul_f32 v[6:7], v[6:7], v[154:155] op_sel_hi:[1,0]
	v_pk_mul_f32 v[4:5], v[4:5], v[154:155] op_sel_hi:[1,0]
	v_pk_mul_f32 v[2:3], v[2:3], v[154:155] op_sel_hi:[1,0]
	v_mul_f32_e32 v171, v171, v154
.Lattn_442T4:
	v_pk_add_f32 v[34:35], v[34:35], v[162:163] op_sel_hi:[1,0] neg_lo:[0,1] neg_hi:[0,1]
	v_pk_add_f32 v[36:37], v[36:37], v[162:163] op_sel_hi:[1,0] neg_lo:[0,1] neg_hi:[0,1]
	v_pk_add_f32 v[38:39], v[38:39], v[162:163] op_sel_hi:[1,0] neg_lo:[0,1] neg_hi:[0,1]
	v_pk_add_f32 v[40:41], v[40:41], v[162:163] op_sel_hi:[1,0] neg_lo:[0,1] neg_hi:[0,1]
	v_pk_add_f32 v[42:43], v[42:43], v[162:163] op_sel_hi:[1,0] neg_lo:[0,1] neg_hi:[0,1]
	v_pk_add_f32 v[44:45], v[44:45], v[162:163] op_sel_hi:[1,0] neg_lo:[0,1] neg_hi:[0,1]
	v_pk_add_f32 v[46:47], v[46:47], v[162:163] op_sel_hi:[1,0] neg_lo:[0,1] neg_hi:[0,1]
	v_pk_add_f32 v[48:49], v[48:49], v[162:163] op_sel_hi:[1,0] neg_lo:[0,1] neg_hi:[0,1]
	v_exp_f32_e32 v34, v34
	v_exp_f32_e32 v35, v35
	v_exp_f32_e32 v36, v36
	v_exp_f32_e32 v37, v37
	v_exp_f32_e32 v38, v38
	v_exp_f32_e32 v39, v39
	v_exp_f32_e32 v40, v40
	v_exp_f32_e32 v41, v41
	v_exp_f32_e32 v42, v42
	v_exp_f32_e32 v43, v43
	v_exp_f32_e32 v44, v44
	v_exp_f32_e32 v45, v45
	v_exp_f32_e32 v46, v46
	v_exp_f32_e32 v47, v47
	v_exp_f32_e32 v48, v48
	v_exp_f32_e32 v49, v49
	v_pk_add_f32 v[154:155], v[34:35], v[36:37]
	v_pk_add_f32 v[156:157], v[38:39], v[40:41]
	v_pk_add_f32 v[158:159], v[42:43], v[44:45]
	v_pk_add_f32 v[160:161], v[46:47], v[48:49]
	v_cvt_pk_bf16_f32 v34, v34, v35
	v_cvt_pk_bf16_f32 v35, v36, v37
	v_cvt_pk_bf16_f32 v36, v38, v39
	v_cvt_pk_bf16_f32 v37, v40, v41
	v_cvt_pk_bf16_f32 v38, v42, v43
	v_cvt_pk_bf16_f32 v39, v44, v45
	v_cvt_pk_bf16_f32 v40, v46, v47
	v_cvt_pk_bf16_f32 v41, v48, v49
	v_pk_add_f32 v[154:155], v[154:155], v[156:157]
	v_pk_add_f32 v[158:159], v[158:159], v[160:161]
	s_nop 0
	v_pk_add_f32 v[154:155], v[154:155], v[158:159]
	s_nop 0
	v_add_f32_e32 v154, v154, v155
	s_waitcnt vmcnt(8)
	v_add_f32_e32 v171, v171, v154
	s_setprio 1
	v_mfma_f32_32x32x16_bf16 v[18:33], v[126:129], v[34:37], v[18:33]
	v_mfma_f32_32x32x16_bf16 v[2:17], v[118:121], v[34:37], v[2:17]
	v_mfma_f32_32x32x16_bf16 v[18:33], v[122:125], v[38:41], v[18:33]
	v_mfma_f32_32x32x16_bf16 v[2:17], v[114:117], v[38:41], v[2:17]
	s_setprio 0
	v_lshl_add_u64 v[160:161], v[200:201], 0, s[10:11]
	global_load_dwordx4 v[126:129], v[160:161], off
	global_load_dwordx4 v[122:125], v[160:161], off offset:1024
	global_load_dwordx4 v[118:121], v[160:161], off offset:2048
	global_load_dwordx4 v[114:117], v[160:161], off offset:3072
	s_add_i32 s7, s53, 5
	s_cmp_gt_u32 s7, s52
	s_cbranch_scc1 .LBB0_446
; DI void dsa_attn_item(const Params& p, int b, int qblk, char* smem) {
;     ...
;     for (int t8 = 0; t8 < 8; ++t8) {
;       const int g = c * 8 + t8;
;       if (g > qblk) break;
;       {
;         const int gn = min(g + 1, qblk);
;         const u16* kr = kfr + (size_t)gn * 2048;
; #pragma unroll
;         for (int ks = 0; ks < 4; ++ks) Kn[ks] = ldg8(kr + ks * 512);
; #pragma unroll
;         for (int dt = 0; dt < 2; ++dt)
; #pragma unroll
;           for (int s = 0; s < 2; ++s) Vn[dt][s] = ldg8(vfr + (size_t)gn * 2048 + (dt * 2 + s) * 512);
;       }
;       const unsigned bits = maskbuf[(buf * 8 + t8) * 64 + lane];
;       f32x16 Sx = zero16();
;       __builtin_amdgcn_s_setprio(1);
; #pragma unroll
;       for (int ks = 0; ks < 4; ++ks) Sx = MFMA(Kf[ks], Qf[ks], Sx);
;       __builtin_amdgcn_s_setprio(0);
;       float sm[16];
; #pragma unroll
;       for (int i = 0; i < 16; ++i) {
;         const unsigned t = (unsigned)__builtin_amdgcn_sbfe((int)bits, i, 1);
;         sm[i] = __uint_as_float((t & __float_as_uint(Sx[i])) | (~t & 0xff800000u));
;       }
;       float mt = fmaxf(fmaxf(fmaxf(sm[0], sm[1]), fmaxf(sm[2], sm[3])), fmaxf(fmaxf(sm[4], sm[5]), fmaxf(sm[6], sm[7])));
;       mt = fmaxf(mt, fmaxf(fmaxf(fmaxf(sm[8], sm[9]), fmaxf(sm[10], sm[11])), fmaxf(fmaxf(sm[12], sm[13]), fmaxf(sm[14], sm[15]))));
;       mt = fmaxf(mt, __shfl_xor(mt, 32));
;       if (__builtin_amdgcn_ballot_w64(mt > mrun + 8.f) != 0ull) {
;         const float mnew = fmaxf(mrun, mt);
;         const float ms = (mnew == -INFINITY) ? 0.f : mnew;
;         const float alpha = __builtin_amdgcn_exp2f(mrun - ms);
;         lrun *= alpha;
;         mrun = mnew;
; #pragma unroll
;         for (int dt = 0; dt < 2; ++dt)
; #pragma unroll
;           for (int i = 0; i < 16; ++i) O[dt][i] *= alpha;
;       }
;       const float msafe = (mrun == -INFINITY) ? 0.f : mrun;
;       float pv[16]; float ps = 0.f;
; #pragma unroll
;       for (int i = 0; i < 16; ++i) { pv[i] = __builtin_amdgcn_exp2f(sm[i] - msafe); ps += pv[i]; }
;       lrun += ps;
;       bf16x8 Pf[2];
; #pragma unroll
;       for (int s = 0; s < 2; ++s) Pf[s] = pack8(pv[8 * s], pv[8 * s + 1], pv[8 * s + 2], pv[8 * s + 3], pv[8 * s + 4], pv[8 * s + 5], pv[8 * s + 6], pv[8 * s + 7]);
;       __builtin_amdgcn_s_setprio(1);
; #pragma unroll
;       for (int dt = 0; dt < 2; ++dt)
; #pragma unroll
	s_add_i32 s60, s7, 2
	s_min_i32 s40, s60, s52
	s_lshl_b64 s[10:11], s[40:41], 12
	s_waitcnt vmcnt(12) lgkmcnt(0)
	s_setprio 1
	v_mfma_f32_32x32x16_bf16 v[34:49], v[66:69], v[98:101], v[238:253]
	v_mfma_f32_32x32x16_bf16 v[34:49], v[70:73], v[102:105], v[34:49]
	v_mfma_f32_32x32x16_bf16 v[34:49], v[74:77], v[106:109], v[34:49]
	v_mfma_f32_32x32x16_bf16 v[34:49], v[78:81], v[110:113], v[34:49]
	s_setprio 0
	v_lshl_add_u64 v[160:161], v[198:199], 0, s[10:11]
	ds_read_b128 v[238:241], v0 offset:24576
	ds_read_b128 v[242:245], v0 offset:25600
	ds_read_b128 v[246:249], v0 offset:26624
	ds_read_b128 v[250:253], v0 offset:27648
	global_load_dwordx4 v[66:69], v[160:161], off
	global_load_dwordx4 v[70:73], v[160:161], off offset:1024
	global_load_dwordx4 v[74:77], v[160:161], off offset:2048
	global_load_dwordx4 v[78:81], v[160:161], off offset:3072
	s_nop 7
	s_nop 3
	v_max_f32_e32 v154, v36, v37
	v_max_f32_e32 v155, v40, v41
	v_max_f32_e32 v156, v42, v43
	v_max_f32_e32 v157, v44, v45
	v_max_f32_e32 v158, v48, v49
	v_max3_f32 v158, v46, v47, v158
	v_max3_f32 v154, v34, v35, v154
	v_max3_f32 v155, v38, v39, v155
	v_max3_f32 v156, v156, v157, v158
	v_max3_f32 v154, v154, v155, v156
	v_mov_b32_e32 v155, v154
	s_nop 1
	v_permlane32_swap_b32_e32 v155, v154
	v_max_f32_e32 v154, v154, v155
	v_cmp_gt_f32_e32 vcc, v154, v229
	s_cbranch_vccz .Lattn_442T5
	v_max_f32_e32 v154, v154, v154
	v_max_f32_e32 v155, v193, v193
	v_max_f32_e32 v155, v155, v154
	v_cmp_neq_f32_e32 vcc, s50, v155
	v_add_f32_e32 v229, 0x41000000, v155
	s_nop 0
	v_cndmask_b32_e32 v162, 0, v155, vcc
	v_sub_f32_e32 v154, v193, v162
	v_exp_f32_e32 v154, v154
	v_mov_b32_e32 v193, v155
	v_pk_mul_f32 v[32:33], v[32:33], v[154:155] op_sel_hi:[1,0]
	v_pk_mul_f32 v[30:31], v[30:31], v[154:155] op_sel_hi:[1,0]
	v_pk_mul_f32 v[28:29], v[28:29], v[154:155] op_sel_hi:[1,0]
	v_pk_mul_f32 v[26:27], v[26:27], v[154:155] op_sel_hi:[1,0]
	v_pk_mul_f32 v[24:25], v[24:25], v[154:155] op_sel_hi:[1,0]
	v_pk_mul_f32 v[22:23], v[22:23], v[154:155] op_sel_hi:[1,0]
	v_pk_mul_f32 v[20:21], v[20:21], v[154:155] op_sel_hi:[1,0]
	v_pk_mul_f32 v[18:19], v[18:19], v[154:155] op_sel_hi:[1,0]
	v_pk_mul_f32 v[16:17], v[16:17], v[154:155] op_sel_hi:[1,0]
	v_pk_mul_f32 v[14:15], v[14:15], v[154:155] op_sel_hi:[1,0]
	v_pk_mul_f32 v[12:13], v[12:13], v[154:155] op_sel_hi:[1,0]
	v_pk_mul_f32 v[10:11], v[10:11], v[154:155] op_sel_hi:[1,0]
	v_pk_mul_f32 v[8:9], v[8:9], v[154:155] op_sel_hi:[1,0]
	v_pk_mul_f32 v[6:7], v[6:7], v[154:155] op_sel_hi:[1,0]
	v_pk_mul_f32 v[4:5], v[4:5], v[154:155] op_sel_hi:[1,0]
	v_pk_mul_f32 v[2:3], v[2:3], v[154:155] op_sel_hi:[1,0]
	v_mul_f32_e32 v171, v171, v154
.Lattn_442T5:
	v_pk_add_f32 v[34:35], v[34:35], v[162:163] op_sel_hi:[1,0] neg_lo:[0,1] neg_hi:[0,1]
	v_pk_add_f32 v[36:37], v[36:37], v[162:163] op_sel_hi:[1,0] neg_lo:[0,1] neg_hi:[0,1]
	v_pk_add_f32 v[38:39], v[38:39], v[162:163] op_sel_hi:[1,0] neg_lo:[0,1] neg_hi:[0,1]
	v_pk_add_f32 v[40:41], v[40:41], v[162:163] op_sel_hi:[1,0] neg_lo:[0,1] neg_hi:[0,1]
	v_pk_add_f32 v[42:43], v[42:43], v[162:163] op_sel_hi:[1,0] neg_lo:[0,1] neg_hi:[0,1]
	v_pk_add_f32 v[44:45], v[44:45], v[162:163] op_sel_hi:[1,0] neg_lo:[0,1] neg_hi:[0,1]
	v_pk_add_f32 v[46:47], v[46:47], v[162:163] op_sel_hi:[1,0] neg_lo:[0,1] neg_hi:[0,1]
	v_pk_add_f32 v[48:49], v[48:49], v[162:163] op_sel_hi:[1,0] neg_lo:[0,1] neg_hi:[0,1]
	v_exp_f32_e32 v34, v34
	v_exp_f32_e32 v35, v35
	v_exp_f32_e32 v36, v36
	v_exp_f32_e32 v37, v37
	v_exp_f32_e32 v38, v38
	v_exp_f32_e32 v39, v39
	v_exp_f32_e32 v40, v40
	v_exp_f32_e32 v41, v41
	v_exp_f32_e32 v42, v42
	v_exp_f32_e32 v43, v43
	v_exp_f32_e32 v44, v44
	v_exp_f32_e32 v45, v45
	v_exp_f32_e32 v46, v46
	v_exp_f32_e32 v47, v47
	v_exp_f32_e32 v48, v48
	v_exp_f32_e32 v49, v49
	v_pk_add_f32 v[154:155], v[34:35], v[36:37]
	v_pk_add_f32 v[156:157], v[38:39], v[40:41]
	v_pk_add_f32 v[158:159], v[42:43], v[44:45]
	v_pk_add_f32 v[160:161], v[46:47], v[48:49]
	v_cvt_pk_bf16_f32 v34, v34, v35
	v_cvt_pk_bf16_f32 v35, v36, v37
	v_cvt_pk_bf16_f32 v36, v38, v39
	v_cvt_pk_bf16_f32 v37, v40, v41
	v_cvt_pk_bf16_f32 v38, v42, v43
	v_cvt_pk_bf16_f32 v39, v44, v45
	v_cvt_pk_bf16_f32 v40, v46, v47
	v_cvt_pk_bf16_f32 v41, v48, v49
	v_pk_add_f32 v[154:155], v[154:155], v[156:157]
	v_pk_add_f32 v[158:159], v[158:159], v[160:161]
	s_nop 0
	v_pk_add_f32 v[154:155], v[154:155], v[158:159]
	s_nop 0
	v_add_f32_e32 v154, v154, v155
	s_waitcnt vmcnt(8)
	v_add_f32_e32 v171, v171, v154
	s_setprio 1
	v_mfma_f32_32x32x16_bf16 v[18:33], v[50:53], v[34:37], v[18:33]
	v_mfma_f32_32x32x16_bf16 v[2:17], v[58:61], v[34:37], v[2:17]
	v_mfma_f32_32x32x16_bf16 v[18:33], v[54:57], v[38:41], v[18:33]
	v_mfma_f32_32x32x16_bf16 v[2:17], v[62:65], v[38:41], v[2:17]
	s_setprio 0
	v_lshl_add_u64 v[160:161], v[200:201], 0, s[10:11]
	global_load_dwordx4 v[50:53], v[160:161], off
	global_load_dwordx4 v[54:57], v[160:161], off offset:1024
	global_load_dwordx4 v[58:61], v[160:161], off offset:2048
	global_load_dwordx4 v[62:65], v[160:161], off offset:3072
	s_add_i32 s7, s53, 6
	s_cmp_gt_u32 s7, s52
	s_cbranch_scc1 .LBB0_446
; #define MFMA(a, b, c) __builtin_amdgcn_mfma_f32_32x32x16_bf16((a), (b), (c), 0, 0, 0)
; DI f32x16 zero16() { f32x16 z; for (int i = 0; i < 16; ++i) z[i] = 0.f; return z; }
; DI void dsa_attn_item(const Params& p, int b, int qblk, char* smem) {
;     ...
;     for (int t8 = 0; t8 < 8; ++t8) {
;       const int g = c * 8 + t8;
;       if (g > qblk) break;
;       {
;         const int gn = min(g + 1, qblk);
;         const u16* kr = kfr + (size_t)gn * 2048;
; #pragma unroll
;         for (int ks = 0; ks < 4; ++ks) Kn[ks] = ldg8(kr + ks * 512);
; #pragma unroll
;         for (int dt = 0; dt < 2; ++dt)
; #pragma unroll
;           for (int s = 0; s < 2; ++s) Vn[dt][s] = ldg8(vfr + (size_t)gn * 2048 + (dt * 2 + s) * 512);
;       }
;       const unsigned bits = maskbuf[(buf * 8 + t8) * 64 + lane];
;       f32x16 Sx = zero16();
;       __builtin_amdgcn_s_setprio(1);
; #pragma unroll
;       for (int ks = 0; ks < 4; ++ks) Sx = MFMA(Kf[ks], Qf[ks], Sx);
;       __builtin_amdgcn_s_setprio(0);
;       float sm[16];
; #pragma unroll
;       for (int i = 0; i < 16; ++i) {
;         const unsigned t = (unsigned)__builtin_amdgcn_sbfe((int)bits, i, 1);
;         sm[i] = __uint_as_float((t & __float_as_uint(Sx[i])) | (~t & 0xff800000u));
;       }
;       float mt = fmaxf(fmaxf(fmaxf(sm[0], sm[1]), fmaxf(sm[2], sm[3])), fmaxf(fmaxf(sm[4], sm[5]), fmaxf(sm[6], sm[7])));
;       mt = fmaxf(mt, fmaxf(fmaxf(fmaxf(sm[8], sm[9]), fmaxf(sm[10], sm[11])), fmaxf(fmaxf(sm[12], sm[13]), fmaxf(sm[14], sm[15]))));
;       mt = fmaxf(mt, __shfl_xor(mt, 32));
;       if (__builtin_amdgcn_ballot_w64(mt > mrun + 8.f) != 0ull) {
;         const float mnew = fmaxf(mrun, mt);
;         const float ms = (mnew == -INFINITY) ? 0.f : mnew;
;         const float alpha = __builtin_amdgcn_exp2f(mrun - ms);
;         lrun *= alpha;
;         mrun = mnew;
; #pragma unroll
;         for (int dt = 0; dt < 2; ++dt)
; #pragma unroll
;           for (int i = 0; i < 16; ++i) O[dt][i] *= alpha;
;       }
	s_add_i32 s60, s7, 2
	s_min_i32 s40, s60, s52
	s_lshl_b64 s[10:11], s[40:41], 12
	s_waitcnt vmcnt(12) lgkmcnt(0)
	s_setprio 1
	v_mfma_f32_32x32x16_bf16 v[34:49], v[150:153], v[98:101], v[238:253]
	v_mfma_f32_32x32x16_bf16 v[34:49], v[146:149], v[102:105], v[34:49]
	v_mfma_f32_32x32x16_bf16 v[34:49], v[142:145], v[106:109], v[34:49]
	v_mfma_f32_32x32x16_bf16 v[34:49], v[138:141], v[110:113], v[34:49]
	s_setprio 0
	v_lshl_add_u64 v[160:161], v[198:199], 0, s[10:11]
	ds_read_b128 v[238:241], v0 offset:28672
	ds_read_b128 v[242:245], v0 offset:29696
	ds_read_b128 v[246:249], v0 offset:30720
	ds_read_b128 v[250:253], v0 offset:31744
	global_load_dwordx4 v[150:153], v[160:161], off
	global_load_dwordx4 v[146:149], v[160:161], off offset:1024
	global_load_dwordx4 v[142:145], v[160:161], off offset:2048
	global_load_dwordx4 v[138:141], v[160:161], off offset:3072
	s_nop 7
	s_nop 3
	v_max_f32_e32 v154, v36, v37
	v_max_f32_e32 v155, v40, v41
	v_max_f32_e32 v156, v42, v43
	v_max_f32_e32 v157, v44, v45
	v_max_f32_e32 v158, v48, v49
	v_max3_f32 v158, v46, v47, v158
	v_max3_f32 v154, v34, v35, v154
	v_max3_f32 v155, v38, v39, v155
	v_max3_f32 v156, v156, v157, v158
	v_max3_f32 v154, v154, v155, v156
	v_mov_b32_e32 v155, v154
	s_nop 1
	v_permlane32_swap_b32_e32 v155, v154
	v_max_f32_e32 v154, v154, v155
	v_cmp_gt_f32_e32 vcc, v154, v229
	s_cbranch_vccz .Lattn_442T6
	v_max_f32_e32 v154, v154, v154
	v_max_f32_e32 v155, v193, v193
	v_max_f32_e32 v155, v155, v154
	v_cmp_neq_f32_e32 vcc, s50, v155
	v_add_f32_e32 v229, 0x41000000, v155
	s_nop 0
	v_cndmask_b32_e32 v162, 0, v155, vcc
	v_sub_f32_e32 v154, v193, v162
	v_exp_f32_e32 v154, v154
	v_mov_b32_e32 v193, v155
	v_pk_mul_f32 v[32:33], v[32:33], v[154:155] op_sel_hi:[1,0]
	v_pk_mul_f32 v[30:31], v[30:31], v[154:155] op_sel_hi:[1,0]
	v_pk_mul_f32 v[28:29], v[28:29], v[154:155] op_sel_hi:[1,0]
	v_pk_mul_f32 v[26:27], v[26:27], v[154:155] op_sel_hi:[1,0]
	v_pk_mul_f32 v[24:25], v[24:25], v[154:155] op_sel_hi:[1,0]
	v_pk_mul_f32 v[22:23], v[22:23], v[154:155] op_sel_hi:[1,0]
	v_pk_mul_f32 v[20:21], v[20:21], v[154:155] op_sel_hi:[1,0]
	v_pk_mul_f32 v[18:19], v[18:19], v[154:155] op_sel_hi:[1,0]
	v_pk_mul_f32 v[16:17], v[16:17], v[154:155] op_sel_hi:[1,0]
	v_pk_mul_f32 v[14:15], v[14:15], v[154:155] op_sel_hi:[1,0]
	v_pk_mul_f32 v[12:13], v[12:13], v[154:155] op_sel_hi:[1,0]
	v_pk_mul_f32 v[10:11], v[10:11], v[154:155] op_sel_hi:[1,0]
	v_pk_mul_f32 v[8:9], v[8:9], v[154:155] op_sel_hi:[1,0]
	v_pk_mul_f32 v[6:7], v[6:7], v[154:155] op_sel_hi:[1,0]
	v_pk_mul_f32 v[4:5], v[4:5], v[154:155] op_sel_hi:[1,0]
	v_pk_mul_f32 v[2:3], v[2:3], v[154:155] op_sel_hi:[1,0]
	v_mul_f32_e32 v171, v171, v154
; #define MFMA(a, b, c) __builtin_amdgcn_mfma_f32_32x32x16_bf16((a), (b), (c), 0, 0, 0)
; DI f32x16 zero16() { f32x16 z; for (int i = 0; i < 16; ++i) z[i] = 0.f; return z; }
; DI void dsa_attn_item(const Params& p, int b, int qblk, char* smem) {
;     ...
;       const unsigned bits = maskbuf[(buf * 8 + t8) * 64 + lane];
;       f32x16 Sx = zero16();
;       __builtin_amdgcn_s_setprio(1);
; #pragma unroll
;       for (int ks = 0; ks < 4; ++ks) Sx = MFMA(Kf[ks], Qf[ks], Sx);
;       __builtin_amdgcn_s_setprio(0);
;       float sm[16];
; #pragma unroll
;       for (int i = 0; i < 16; ++i) {
;         const unsigned t = (unsigned)__builtin_amdgcn_sbfe((int)bits, i, 1);
;         sm[i] = __uint_as_float((t & __float_as_uint(Sx[i])) | (~t & 0xff800000u));
;       }
;       float mt = fmaxf(fmaxf(fmaxf(sm[0], sm[1]), fmaxf(sm[2], sm[3])), fmaxf(fmaxf(sm[4], sm[5]), fmaxf(sm[6], sm[7])));
;       mt = fmaxf(mt, fmaxf(fmaxf(fmaxf(sm[8], sm[9]), fmaxf(sm[10], sm[11])), fmaxf(fmaxf(sm[12], sm[13]), fmaxf(sm[14], sm[15]))));
;       mt = fmaxf(mt, __shfl_xor(mt, 32));
;       if (__builtin_amdgcn_ballot_w64(mt > mrun + 8.f) != 0ull) {
;         const float mnew = fmaxf(mrun, mt);
;         const float ms = (mnew == -INFINITY) ? 0.f : mnew;
;         const float alpha = __builtin_amdgcn_exp2f(mrun - ms);
;         lrun *= alpha;
;         mrun = mnew;
; #pragma unroll
;         for (int dt = 0; dt < 2; ++dt)
; #pragma unroll
;           for (int i = 0; i < 16; ++i) O[dt][i] *= alpha;
;       }
;       const float msafe = (mrun == -INFINITY) ? 0.f : mrun;
;       float pv[16]; float ps = 0.f;
; #pragma unroll
;       for (int i = 0; i < 16; ++i) { pv[i] = __builtin_amdgcn_exp2f(sm[i] - msafe); ps += pv[i]; }
;       lrun += ps;
;       bf16x8 Pf[2];
; #pragma unroll
;       for (int s = 0; s < 2; ++s) Pf[s] = pack8(pv[8 * s], pv[8 * s + 1], pv[8 * s + 2], pv[8 * s + 3], pv[8 * s + 4], pv[8 * s + 5], pv[8 * s + 6], pv[8 * s + 7]);
;       __builtin_amdgcn_s_setprio(1);
; #pragma unroll
;       for (int dt = 0; dt < 2; ++dt)
; #pragma unroll
;         for (int s = 0; s < 2; ++s) O[dt] = MFMA(Vf[dt][s], Pf[s], O[dt]);
;       __builtin_amdgcn_s_setprio(0);
; #pragma unroll
;       for (int ks = 0; ks < 4; ++ks) Kf[ks] = Kn[ks];
; #pragma unroll
;       for (int dt = 0; dt < 2; ++dt)
; #pragma unroll
;         for (int s = 0; s < 2; ++s) Vf[dt][s] = Vn[dt][s];
;     }
;   }
.Lattn_442T6:
	v_pk_add_f32 v[34:35], v[34:35], v[162:163] op_sel_hi:[1,0] neg_lo:[0,1] neg_hi:[0,1]
	v_pk_add_f32 v[36:37], v[36:37], v[162:163] op_sel_hi:[1,0] neg_lo:[0,1] neg_hi:[0,1]
	v_pk_add_f32 v[38:39], v[38:39], v[162:163] op_sel_hi:[1,0] neg_lo:[0,1] neg_hi:[0,1]
	v_pk_add_f32 v[40:41], v[40:41], v[162:163] op_sel_hi:[1,0] neg_lo:[0,1] neg_hi:[0,1]
	v_pk_add_f32 v[42:43], v[42:43], v[162:163] op_sel_hi:[1,0] neg_lo:[0,1] neg_hi:[0,1]
	v_pk_add_f32 v[44:45], v[44:45], v[162:163] op_sel_hi:[1,0] neg_lo:[0,1] neg_hi:[0,1]
	v_pk_add_f32 v[46:47], v[46:47], v[162:163] op_sel_hi:[1,0] neg_lo:[0,1] neg_hi:[0,1]
	v_pk_add_f32 v[48:49], v[48:49], v[162:163] op_sel_hi:[1,0] neg_lo:[0,1] neg_hi:[0,1]
	v_exp_f32_e32 v34, v34
	v_exp_f32_e32 v35, v35
	v_exp_f32_e32 v36, v36
	v_exp_f32_e32 v37, v37
	v_exp_f32_e32 v38, v38
	v_exp_f32_e32 v39, v39
	v_exp_f32_e32 v40, v40
	v_exp_f32_e32 v41, v41
	v_exp_f32_e32 v42, v42
	v_exp_f32_e32 v43, v43
	v_exp_f32_e32 v44, v44
	v_exp_f32_e32 v45, v45
	v_exp_f32_e32 v46, v46
	v_exp_f32_e32 v47, v47
	v_exp_f32_e32 v48, v48
	v_exp_f32_e32 v49, v49
	v_pk_add_f32 v[154:155], v[34:35], v[36:37]
	v_pk_add_f32 v[156:157], v[38:39], v[40:41]
	v_pk_add_f32 v[158:159], v[42:43], v[44:45]
	v_pk_add_f32 v[160:161], v[46:47], v[48:49]
	v_cvt_pk_bf16_f32 v34, v34, v35
	v_cvt_pk_bf16_f32 v35, v36, v37
	v_cvt_pk_bf16_f32 v36, v38, v39
	v_cvt_pk_bf16_f32 v37, v40, v41
	v_cvt_pk_bf16_f32 v38, v42, v43
	v_cvt_pk_bf16_f32 v39, v44, v45
	v_cvt_pk_bf16_f32 v40, v46, v47
	v_cvt_pk_bf16_f32 v41, v48, v49
	v_pk_add_f32 v[154:155], v[154:155], v[156:157]
	v_pk_add_f32 v[158:159], v[158:159], v[160:161]
	s_nop 0
	v_pk_add_f32 v[154:155], v[154:155], v[158:159]
	s_nop 0
	v_add_f32_e32 v154, v154, v155
	s_waitcnt vmcnt(8)
	v_add_f32_e32 v171, v171, v154
	s_setprio 1
	v_mfma_f32_32x32x16_bf16 v[18:33], v[126:129], v[34:37], v[18:33]
	v_mfma_f32_32x32x16_bf16 v[2:17], v[118:121], v[34:37], v[2:17]
	v_mfma_f32_32x32x16_bf16 v[18:33], v[122:125], v[38:41], v[18:33]
	v_mfma_f32_32x32x16_bf16 v[2:17], v[114:117], v[38:41], v[2:17]
	s_setprio 0
	v_lshl_add_u64 v[160:161], v[200:201], 0, s[10:11]
	global_load_dwordx4 v[126:129], v[160:161], off
	global_load_dwordx4 v[122:125], v[160:161], off offset:1024
	global_load_dwordx4 v[118:121], v[160:161], off offset:2048
	global_load_dwordx4 v[114:117], v[160:161], off offset:3072
	s_add_i32 s7, s53, 7
	s_cmp_gt_u32 s7, s52
	s_cbranch_scc1 .LBB0_446
	s_waitcnt vmcnt(12) lgkmcnt(0)
	s_setprio 1
	v_mfma_f32_32x32x16_bf16 v[34:49], v[66:69], v[98:101], v[238:253]
	v_mfma_f32_32x32x16_bf16 v[34:49], v[70:73], v[102:105], v[34:49]
	v_mfma_f32_32x32x16_bf16 v[34:49], v[74:77], v[106:109], v[34:49]
	v_mfma_f32_32x32x16_bf16 v[34:49], v[78:81], v[110:113], v[34:49]
	s_setprio 0
	s_nop 7
	s_nop 3
	v_max_f32_e32 v154, v36, v37
	v_max_f32_e32 v155, v40, v41
	v_max_f32_e32 v156, v42, v43
	v_max_f32_e32 v157, v44, v45
	v_max_f32_e32 v158, v48, v49
	v_max3_f32 v158, v46, v47, v158
	v_max3_f32 v154, v34, v35, v154
	v_max3_f32 v155, v38, v39, v155
	v_max3_f32 v156, v156, v157, v158
	v_max3_f32 v154, v154, v155, v156
	v_mov_b32_e32 v155, v154
	s_nop 1
	v_permlane32_swap_b32_e32 v155, v154
	v_max_f32_e32 v154, v154, v155
	v_cmp_gt_f32_e32 vcc, v154, v229
	s_cbranch_vccz .Lattn_442T7
	v_max_f32_e32 v154, v154, v154
	v_max_f32_e32 v155, v193, v193
	v_max_f32_e32 v155, v155, v154
	v_cmp_neq_f32_e32 vcc, s50, v155
	v_add_f32_e32 v229, 0x41000000, v155
	s_nop 0
	v_cndmask_b32_e32 v162, 0, v155, vcc
	v_sub_f32_e32 v154, v193, v162
	v_exp_f32_e32 v154, v154
	v_mov_b32_e32 v193, v155
	v_pk_mul_f32 v[32:33], v[32:33], v[154:155] op_sel_hi:[1,0]
	v_pk_mul_f32 v[30:31], v[30:31], v[154:155] op_sel_hi:[1,0]
	v_pk_mul_f32 v[28:29], v[28:29], v[154:155] op_sel_hi:[1,0]
	v_pk_mul_f32 v[26:27], v[26:27], v[154:155] op_sel_hi:[1,0]
	v_pk_mul_f32 v[24:25], v[24:25], v[154:155] op_sel_hi:[1,0]
	v_pk_mul_f32 v[22:23], v[22:23], v[154:155] op_sel_hi:[1,0]
	v_pk_mul_f32 v[20:21], v[20:21], v[154:155] op_sel_hi:[1,0]
	v_pk_mul_f32 v[18:19], v[18:19], v[154:155] op_sel_hi:[1,0]
	v_pk_mul_f32 v[16:17], v[16:17], v[154:155] op_sel_hi:[1,0]
	v_pk_mul_f32 v[14:15], v[14:15], v[154:155] op_sel_hi:[1,0]
	v_pk_mul_f32 v[12:13], v[12:13], v[154:155] op_sel_hi:[1,0]
	v_pk_mul_f32 v[10:11], v[10:11], v[154:155] op_sel_hi:[1,0]
	v_pk_mul_f32 v[8:9], v[8:9], v[154:155] op_sel_hi:[1,0]
	v_pk_mul_f32 v[6:7], v[6:7], v[154:155] op_sel_hi:[1,0]
	v_pk_mul_f32 v[4:5], v[4:5], v[154:155] op_sel_hi:[1,0]
	v_pk_mul_f32 v[2:3], v[2:3], v[154:155] op_sel_hi:[1,0]
	v_mul_f32_e32 v171, v171, v154
.Lattn_442T7:
	v_pk_add_f32 v[34:35], v[34:35], v[162:163] op_sel_hi:[1,0] neg_lo:[0,1] neg_hi:[0,1]
	v_pk_add_f32 v[36:37], v[36:37], v[162:163] op_sel_hi:[1,0] neg_lo:[0,1] neg_hi:[0,1]
	v_pk_add_f32 v[38:39], v[38:39], v[162:163] op_sel_hi:[1,0] neg_lo:[0,1] neg_hi:[0,1]
	v_pk_add_f32 v[40:41], v[40:41], v[162:163] op_sel_hi:[1,0] neg_lo:[0,1] neg_hi:[0,1]
	v_pk_add_f32 v[42:43], v[42:43], v[162:163] op_sel_hi:[1,0] neg_lo:[0,1] neg_hi:[0,1]
	v_pk_add_f32 v[44:45], v[44:45], v[162:163] op_sel_hi:[1,0] neg_lo:[0,1] neg_hi:[0,1]
	v_pk_add_f32 v[46:47], v[46:47], v[162:163] op_sel_hi:[1,0] neg_lo:[0,1] neg_hi:[0,1]
	v_pk_add_f32 v[48:49], v[48:49], v[162:163] op_sel_hi:[1,0] neg_lo:[0,1] neg_hi:[0,1]
	v_exp_f32_e32 v34, v34
	v_exp_f32_e32 v35, v35
	v_exp_f32_e32 v36, v36
	v_exp_f32_e32 v37, v37
	v_exp_f32_e32 v38, v38
	v_exp_f32_e32 v39, v39
	v_exp_f32_e32 v40, v40
	v_exp_f32_e32 v41, v41
	v_exp_f32_e32 v42, v42
	v_exp_f32_e32 v43, v43
	v_exp_f32_e32 v44, v44
	v_exp_f32_e32 v45, v45
	v_exp_f32_e32 v46, v46
	v_exp_f32_e32 v47, v47
	v_exp_f32_e32 v48, v48
	v_exp_f32_e32 v49, v49
	v_pk_add_f32 v[154:155], v[34:35], v[36:37]
	v_pk_add_f32 v[156:157], v[38:39], v[40:41]
	v_pk_add_f32 v[158:159], v[42:43], v[44:45]
	v_pk_add_f32 v[160:161], v[46:47], v[48:49]
	v_cvt_pk_bf16_f32 v34, v34, v35
	v_cvt_pk_bf16_f32 v35, v36, v37
	v_cvt_pk_bf16_f32 v36, v38, v39
	v_cvt_pk_bf16_f32 v37, v40, v41
	v_cvt_pk_bf16_f32 v38, v42, v43
	v_cvt_pk_bf16_f32 v39, v44, v45
	v_cvt_pk_bf16_f32 v40, v46, v47
	v_cvt_pk_bf16_f32 v41, v48, v49
	v_pk_add_f32 v[154:155], v[154:155], v[156:157]
	v_pk_add_f32 v[158:159], v[158:159], v[160:161]
	s_nop 0
	v_pk_add_f32 v[154:155], v[154:155], v[158:159]
	s_nop 0
	v_add_f32_e32 v154, v154, v155
	s_waitcnt vmcnt(8)
	v_add_f32_e32 v171, v171, v154
	s_setprio 1
	v_mfma_f32_32x32x16_bf16 v[18:33], v[50:53], v[34:37], v[18:33]
	v_mfma_f32_32x32x16_bf16 v[2:17], v[58:61], v[34:37], v[2:17]
	v_mfma_f32_32x32x16_bf16 v[18:33], v[54:57], v[38:41], v[18:33]
	v_mfma_f32_32x32x16_bf16 v[2:17], v[62:65], v[38:41], v[2:17]
	s_setprio 0
.LBB0_446:
	s_xor_b64 s[44:45], s[44:45], -1
	s_add_i32 s53, s53, 8
	s_cmp_lg_u32 s54, s5
	s_cbranch_scc0 .LBB0_424
	s_waitcnt vmcnt(8)
	v_mov_b64_e32 v[156:157], v[132:133]
	v_mov_b64_e32 v[160:161], v[136:137]
	v_mov_b64_e32 v[154:155], v[130:131]
	v_mov_b64_e32 v[158:159], v[134:135]
	s_mov_b32 s54, s55
	s_branch .LBB0_434
